# prologue fence v1 plus GEMM phase start: the six K-tile-1 stage loads are issued together with the K-tile-0 loads (first wait vmcnt(2)+barrier moved below them as vmcnt(8))
# baseline (speedup 1.0000x reference)
; #define PG8_STAGE(bufoff, gbase, voff) do { _Pragma("unroll") for (int _i = 0; _i < 2; ++_i) \
;         __builtin_amdgcn_global_load_lds((const unsigned*)((const char*)(gbase) + (voff)[_i]), (PG8_LAS unsigned*)(lds + (bufoff) + ldsw + _i * 8192), 16, 0, 0); } while (0)
; #define PG8_WAIT_V(n) asm volatile("s_waitcnt vmcnt(" #n ")" ::: "memory")
; #define PG8_BAR __builtin_amdgcn_s_barrier()
; template <class Epi, class Sched, bool ALIGN_EPI = false, bool SP2 = false>
; __device__ __forceinline__ void gemm_phase(PG8_LAS unsigned char* lds, const Gemm g, const Sched& S, const Epi& E) {
;     ...
;         PG8_STAGE(PG8_SB(0, 0), cB, voffB); PG8_STAGE(PG8_SB(0, 1), cB + hstep, voffB); PG8_STAGE(PG8_SA(0, 0), cA, voffA); PG8_STAGE(PG8_SA(0, 1), cA + hstep, voffA);
;         if (wr == 1) PG8_BAR;
;         PG8_WAIT_V(2); PG8_BAR;
;         PG8_STAGE(PG8_SB(1, 0), cB + kstep, voffB); PG8_STAGE(PG8_SA(1, 0), cA + kstep, voffA); PG8_STAGE(PG8_SB(1, 1), cB + hstep + kstep, voffB);
;         PG8_WAIT_V(6); PG8_BAR;
.LBB0_104:
	v_mov_b32_e32 v135, v80
	v_lshl_add_u64 v[8:9], s[46:47], 0, v[134:135]
	v_mov_b32_e32 v131, v80
	v_readlane_b32 s44, v249, 53
	s_lshl_b32 s5, s5, 5
	v_lshl_add_u64 v[10:11], s[46:47], 0, v[130:131]
	v_mov_b32_e32 v137, v80
	v_readlane_b32 s45, v249, 54
	s_and_b32 s55, s5, 0x60
	s_add_i32 m0, s50, 0x18000
	v_lshl_add_u64 v[8:9], v[8:9], 0, s[40:41]
	v_lshl_add_u64 v[12:13], s[44:45], 0, v[136:137]
	v_mov_b32_e32 v133, v80
	s_lshl_b32 s54, s12, 6
	s_lshl_b32 s14, s12, 13
	s_lshl_b32 s5, s55, 7
	global_load_lds_dwordx4 v[8:9], off
	v_lshl_add_u64 v[8:9], v[10:11], 0, s[40:41]
	s_add_i32 m0, s50, 0x1a000
	s_add_i32 s56, s50, 0x8000
	s_add_i32 s57, s50, 0xa000
	v_lshl_add_u64 v[14:15], s[44:45], 0, v[132:133]
	global_load_lds_dwordx4 v[8:9], off
	v_lshl_add_u64 v[8:9], v[12:13], 0, s[40:41]
	s_mov_b32 m0, s56
	s_add_u32 s12, s46, 0x40080
	global_load_lds_dwordx4 v[8:9], off
	v_lshl_add_u64 v[8:9], v[14:15], 0, s[40:41]
	s_mov_b32 m0, s57
	s_addc_u32 s13, s47, 0
	global_load_lds_dwordx4 v[8:9], off
	s_add_i32 m0, s50, 0x1c000
	v_lshl_add_u64 v[8:9], s[12:13], 0, v[134:135]
	global_load_lds_dwordx4 v[8:9], off
	v_lshl_add_u64 v[8:9], s[12:13], 0, v[130:131]
	s_add_i32 m0, s50, 0x1e000
	v_bfe_u32 v142, v0, 4, 2
	global_load_lds_dwordx4 v[8:9], off
	v_and_b32_e32 v81, 15, v0
	v_lshlrev_b32_e32 v7, 4, v142
	v_lshlrev_b32_e32 v0, 2, v0
	v_lshl_or_b32 v7, v81, 6, v7
	v_and_b32_e32 v0, 32, v0
	v_bitop3_b32 v8, v7, s14, v0 bitop3:0xde
	v_bitop3_b32 v143, v7, s5, v0 bitop3:0xde
	v_lshlrev_b32_e32 v0, 14, v5
	v_and_b32_e32 v0, 0xffff8000, v0
	v_lshl_add_u32 v0, v4, 11, v0
	v_and_b32_e32 v4, 1, v5
	v_lshl_or_b32 v0, v4, 6, v0
	v_lshl_add_u32 v138, v6, 1, v0
	v_lshlrev_b32_e32 v0, 14, v1
	v_and_b32_e32 v0, 0xffff8000, v0
	s_waitcnt vmcnt(8)
	s_barrier
	s_waitcnt vmcnt(6)
	v_lshl_add_u32 v0, v2, 11, v0
	v_and_b32_e32 v1, 1, v1
	s_cmpk_lt_u32 s4, 0x100
	v_lshl_or_b32 v0, v1, 6, v0
	v_readlane_b32 s4, v249, 51
	s_cselect_b64 s[12:13], -1, 0
	v_mov_b32_e32 v139, v80
	v_lshl_add_u32 v140, v3, 1, v0
	v_mov_b32_e32 v141, v80
	s_mov_b32 s58, 0
	s_mov_b32 s59, -1
	v_add_u32_e32 v144, 0, v8
	v_readlane_b32 s60, v249, 48
	s_mov_b32 s61, s4
	s_barrier
	v_readlane_b32 s5, v249, 52
	s_branch .LBB0_107

; #define PG8_STAGE(bufoff, gbase, voff) do { _Pragma("unroll") for (int _i = 0; _i < 2; ++_i) \
;         __builtin_amdgcn_global_load_lds((const unsigned*)((const char*)(gbase) + (voff)[_i]), (PG8_LAS unsigned*)(lds + (bufoff) + ldsw + _i * 8192), 16, 0, 0); } while (0)
; #define PG8_WAIT_V(n) asm volatile("s_waitcnt vmcnt(" #n ")" ::: "memory")
; #define PG8_BAR __builtin_amdgcn_s_barrier()
; template <class Epi, class Sched, bool ALIGN_EPI = false, bool SP2 = false>
; __device__ __forceinline__ void gemm_phase(PG8_LAS unsigned char* lds, const Gemm g, const Sched& S, const Epi& E) {
;     ...
;         PG8_STAGE(PG8_SB(0, 0), cB, voffB); PG8_STAGE(PG8_SB(0, 1), cB + hstep, voffB); PG8_STAGE(PG8_SA(0, 0), cA, voffA); PG8_STAGE(PG8_SA(0, 1), cA + hstep, voffA);
;         if (wr == 1) PG8_BAR;
;         PG8_WAIT_V(2); PG8_BAR;
;         PG8_STAGE(PG8_SB(1, 0), cB + kstep, voffB); PG8_STAGE(PG8_SA(1, 0), cA + kstep, voffA); PG8_STAGE(PG8_SB(1, 1), cB + hstep + kstep, voffB);
;         PG8_WAIT_V(6); PG8_BAR;
.LBB0_123:
	v_bfe_u32 v145, v6, 4, 2
	s_lshl_b32 s5, s5, 5
	v_mov_b32_e32 v135, v80
	v_and_b32_e32 v81, 15, v6
	v_lshlrev_b32_e32 v7, 4, v145
	v_lshlrev_b32_e32 v6, 2, v6
	s_and_b32 s58, s5, 0x60
	v_lshl_add_u64 v[8:9], s[48:49], 0, v[134:135]
	v_mov_b32_e32 v131, v80
	v_readlane_b32 s46, v249, 62
	s_lshl_b32 s57, s14, 6
	v_lshl_or_b32 v7, v81, 6, v7
	s_lshl_b32 s14, s14, 13
	v_and_b32_e32 v6, 32, v6
	s_lshl_b32 s5, s58, 7
	v_lshl_add_u64 v[10:11], s[48:49], 0, v[130:131]
	v_mov_b32_e32 v137, v80
	v_readlane_b32 s47, v249, 63
	v_bitop3_b32 v16, v7, s14, v6 bitop3:0xde
	v_bitop3_b32 v148, v7, s5, v6 bitop3:0xde
	s_add_i32 m0, s53, 0x18000
	v_lshl_add_u64 v[6:7], v[8:9], 0, s[40:41]
	v_lshl_add_u64 v[12:13], s[46:47], 0, v[136:137]
	v_mov_b32_e32 v133, v80
	global_load_lds_dwordx4 v[6:7], off
	v_lshl_add_u64 v[6:7], v[10:11], 0, s[40:41]
	s_add_i32 m0, s53, 0x1a000
	s_add_i32 s59, s53, 0x8000
	s_add_i32 s60, s53, 0xa000
	v_lshl_add_u64 v[14:15], s[46:47], 0, v[132:133]
	global_load_lds_dwordx4 v[6:7], off
	v_lshl_add_u64 v[6:7], v[12:13], 0, s[40:41]
	s_mov_b32 m0, s59
	s_add_u32 s14, s48, 0x40080
	global_load_lds_dwordx4 v[6:7], off
	v_lshl_add_u64 v[6:7], v[14:15], 0, s[40:41]
	s_mov_b32 m0, s60
	s_addc_u32 s15, s49, 0
	global_load_lds_dwordx4 v[6:7], off
	s_add_i32 m0, s53, 0x1c000
	v_lshl_add_u64 v[6:7], s[14:15], 0, v[134:135]
	global_load_lds_dwordx4 v[6:7], off
	v_lshl_add_u64 v[6:7], s[14:15], 0, v[130:131]
	s_add_i32 m0, s53, 0x1e000
	s_cmpk_lt_u32 s4, 0x100
	global_load_lds_dwordx4 v[6:7], off
	v_lshlrev_b32_e32 v6, 14, v4
	v_and_b32_e32 v6, 0xffff8000, v6
	v_lshl_add_u32 v3, v3, 11, v6
	v_and_b32_e32 v4, 1, v4
	v_lshl_or_b32 v3, v4, 6, v3
	v_lshl_add_u32 v138, v5, 1, v3
	v_lshlrev_b32_e32 v3, 14, v0
	v_and_b32_e32 v3, 0xffff8000, v3
	s_waitcnt vmcnt(8)
	s_barrier
	s_waitcnt vmcnt(6)
	v_lshl_add_u32 v1, v1, 11, v3
	v_and_b32_e32 v0, 1, v0
	v_lshl_or_b32 v0, v0, 6, v1
	v_readlane_b32 s4, v249, 60
	s_cselect_b64 s[14:15], -1, 0
	v_mov_b32_e32 v139, v80
	v_lshl_add_u32 v140, v2, 1, v0
	v_mov_b32_e32 v141, v80
	s_mov_b32 s61, 0
	s_mov_b32 s62, -1
	v_add_u32_e32 v149, 0, v16
	v_readlane_b32 s63, v249, 57
	s_mov_b32 s20, s4
	s_barrier
	v_readlane_b32 s5, v249, 61
	s_branch .LBB0_126

; #define PG8_STAGE(bufoff, gbase, voff) do { _Pragma("unroll") for (int _i = 0; _i < 2; ++_i) \
;         __builtin_amdgcn_global_load_lds((const unsigned*)((const char*)(gbase) + (voff)[_i]), (PG8_LAS unsigned*)(lds + (bufoff) + ldsw + _i * 8192), 16, 0, 0); } while (0)
; #define PG8_WAIT_V(n) asm volatile("s_waitcnt vmcnt(" #n ")" ::: "memory")
; #define PG8_BAR __builtin_amdgcn_s_barrier()
; template <class Epi, class Sched, bool ALIGN_EPI = false, bool SP2 = false>
; __device__ __forceinline__ void gemm_phase(PG8_LAS unsigned char* lds, const Gemm g, const Sched& S, const Epi& E) {
;     ...
;         PG8_STAGE(PG8_SB(0, 0), cB, voffB); PG8_STAGE(PG8_SB(0, 1), cB + hstep, voffB); PG8_STAGE(PG8_SA(0, 0), cA, voffA); PG8_STAGE(PG8_SA(0, 1), cA + hstep, voffA);
;         if (wr == 1) PG8_BAR;
;         PG8_WAIT_V(2); PG8_BAR;
;         PG8_STAGE(PG8_SB(1, 0), cB + kstep, voffB); PG8_STAGE(PG8_SA(1, 0), cA + kstep, voffA); PG8_STAGE(PG8_SB(1, 1), cB + hstep + kstep, voffB);
;         PG8_WAIT_V(6); PG8_BAR;
.LBB0_150:
	v_mov_b32_e32 v179, v80
	v_bfe_u32 v198, v1, 4, 2
	v_lshl_add_u64 v[8:9], s[48:49], 0, v[178:179]
	v_mov_b32_e32 v183, v80
	v_and_b32_e32 v81, 15, v1
	v_lshlrev_b32_e32 v7, 4, v198
	v_lshlrev_b32_e32 v1, 2, v1
	v_lshl_add_u64 v[10:11], s[48:49], 0, v[182:183]
	v_mov_b32_e32 v177, v80
	s_and_b32 s58, s15, 3
	v_lshl_or_b32 v7, v81, 6, v7
	s_lshl_b32 s5, s16, 13
	v_and_b32_e32 v1, 32, v1
	s_add_i32 m0, s11, 0x18000
	v_lshl_add_u64 v[8:9], v[8:9], 0, s[40:41]
	v_lshl_add_u64 v[12:13], s[6:7], 0, v[176:177]
	v_mov_b32_e32 v181, v80
	s_lshl_b32 s59, s16, 6
	v_bitop3_b32 v16, v7, s5, v1 bitop3:0xde
	s_lshl_b32 s60, s58, 5
	s_lshl_b32 s5, s58, 12
	global_load_lds_dwordx4 v[8:9], off
	v_lshl_add_u64 v[8:9], v[10:11], 0, s[40:41]
	s_add_i32 m0, s11, 0x1a000
	s_add_i32 s61, s11, 0x8000
	s_add_i32 s62, s11, 0xa000
	v_lshl_add_u64 v[14:15], s[6:7], 0, v[180:181]
	global_load_lds_dwordx4 v[8:9], off
	v_lshl_add_u64 v[8:9], v[12:13], 0, s[40:41]
	s_mov_b32 m0, s61
	s_add_u32 s16, s48, 0x40080
	global_load_lds_dwordx4 v[8:9], off
	v_lshl_add_u64 v[8:9], v[14:15], 0, s[40:41]
	s_mov_b32 m0, s62
	s_addc_u32 s17, s49, 0
	global_load_lds_dwordx4 v[8:9], off
	s_add_i32 m0, s11, 0x1c000
	v_lshl_add_u64 v[8:9], s[16:17], 0, v[178:179]
	global_load_lds_dwordx4 v[8:9], off
	v_lshl_add_u64 v[8:9], s[16:17], 0, v[182:183]
	s_add_i32 m0, s11, 0x1e000
	v_bitop3_b32 v199, v7, s5, v1 bitop3:0xde
	global_load_lds_dwordx4 v[8:9], off
	v_lshlrev_b32_e32 v1, 14, v0
	v_and_b32_e32 v1, 0xffff8000, v1
	v_lshl_add_u32 v1, v2, 11, v1
	v_and_b32_e32 v0, 1, v0
	v_lshl_or_b32 v0, v0, 6, v1
	v_lshl_add_u32 v184, v3, 1, v0
	v_lshlrev_b32_e32 v0, 14, v4
	v_and_b32_e32 v0, 0xffff8000, v0
	s_waitcnt vmcnt(8)
	s_barrier
	s_waitcnt vmcnt(6)
	v_lshl_add_u32 v0, v5, 11, v0
	v_and_b32_e32 v1, 1, v4
	s_cmpk_lt_u32 s14, 0x100
	v_lshl_or_b32 v0, v1, 6, v0
	s_cselect_b64 s[14:15], -1, 0
	s_lshl_b32 s63, s58, 6
	v_mov_b32_e32 v185, v80
	v_lshl_add_u32 v186, v6, 1, v0
	v_mov_b32_e32 v187, v80
	s_mov_b32 s64, 0
	s_mov_b32 s66, -1
	v_add_u32_e32 v200, 0, v16
	s_barrier
	s_branch .LBB0_153

; #define PG8_STAGE(bufoff, gbase, voff) do { _Pragma("unroll") for (int _i = 0; _i < 2; ++_i) \
;         __builtin_amdgcn_global_load_lds((const unsigned*)((const char*)(gbase) + (voff)[_i]), (PG8_LAS unsigned*)(lds + (bufoff) + ldsw + _i * 8192), 16, 0, 0); } while (0)
; #define PG8_WAIT_V(n) asm volatile("s_waitcnt vmcnt(" #n ")" ::: "memory")
; #define PG8_BAR __builtin_amdgcn_s_barrier()
; template <class Epi, class Sched, bool ALIGN_EPI = false, bool SP2 = false>
; __device__ __forceinline__ void gemm_phase(PG8_LAS unsigned char* lds, const Gemm g, const Sched& S, const Epi& E) {
;     ...
;         PG8_STAGE(PG8_SB(0, 0), cB, voffB); PG8_STAGE(PG8_SB(0, 1), cB + hstep, voffB); PG8_STAGE(PG8_SA(0, 0), cA, voffA); PG8_STAGE(PG8_SA(0, 1), cA + hstep, voffA);
;         if (wr == 1) PG8_BAR;
;         PG8_WAIT_V(2); PG8_BAR;
;         PG8_STAGE(PG8_SB(1, 0), cB + kstep, voffB); PG8_STAGE(PG8_SA(1, 0), cA + kstep, voffA); PG8_STAGE(PG8_SB(1, 1), cB + hstep + kstep, voffB);
;         PG8_WAIT_V(6); PG8_BAR;
.LBB0_369:
	s_add_i32 m0, s58, 0x18000
	v_lshl_add_u64 v[0:1], v[0:1], 0, s[40:41]
	global_load_lds_dwordx4 v[0:1], off
	v_lshl_add_u64 v[0:1], v[2:3], 0, s[40:41]
	s_add_i32 m0, s58, 0x1a000
	s_add_i32 s66, s58, 0x8000
	global_load_lds_dwordx4 v[0:1], off
	v_lshl_add_u64 v[0:1], v[8:9], 0, s[40:41]
	s_mov_b32 m0, s66
	s_add_i32 s67, s58, 0xa000
	global_load_lds_dwordx4 v[0:1], off
	v_lshl_add_u64 v[0:1], v[10:11], 0, s[40:41]
	s_mov_b32 m0, s67
	s_and_b32 s62, s5, 3
	global_load_lds_dwordx4 v[0:1], off
	s_add_i32 m0, s58, 0x1c000
	v_lshl_add_u64 v[0:1], v[4:5], 0, s[40:41]
	global_load_lds_dwordx4 v[0:1], off
	v_lshl_add_u64 v[0:1], v[6:7], 0, s[40:41]
	s_add_i32 m0, s58, 0x1e000
	s_lshl_b32 s5, s5, 9
	global_load_lds_dwordx4 v[0:1], off
	s_add_i32 s5, s5, 0
	v_lshlrev_b32_e32 v1, 7, v12
	v_bfe_u32 v81, v12, 4, 2
	s_add_i32 s68, s5, 0x20000
	v_lshlrev_b32_e32 v0, 9, v12
	v_and_b32_e32 v1, 0x180, v1
	s_movk_i32 s5, 0xf800
	v_and_b32_e32 v208, 15, v12
	v_lshlrev_b32_e32 v19, 4, v81
	v_lshlrev_b32_e32 v20, 2, v12
	v_and_or_b32 v210, v0, s5, v1
	v_add_u32_e32 v0, v18, v16
	s_lshr_b32 s63, s6, 6
	v_lshl_or_b32 v19, v208, 6, v19
	s_lshl_b32 s6, s7, 13
	v_and_b32_e32 v20, 32, v20
	v_add_lshl_u32 v0, v0, v17, 1
	v_mov_b32_e32 v1, v80
	s_lshl_b32 s64, s7, 6
	v_bitop3_b32 v21, v19, s6, v20 bitop3:0xde
	s_lshl_b32 s65, s62, 5
	s_lshl_b32 s6, s62, 12
	s_waitcnt vmcnt(8)
	s_barrier
	s_waitcnt vmcnt(6)
	v_lshl_add_u64 v[180:181], s[14:15], 0, v[0:1]
	v_add_u32_e32 v0, v15, v13
	s_cmpk_lt_u32 s4, 0x100
	v_add_lshl_u32 v0, v0, v14, 1
	v_bitop3_b32 v209, v19, s6, v20 bitop3:0xde
	s_cselect_b64 s[18:19], -1, 0
	s_mov_b32 s13, s12
	v_lshl_add_u64 v[182:183], s[14:15], 0, v[0:1]
	s_add_i32 s15, s63, -2
	s_add_i32 s69, s63, -8
	s_mov_b32 s70, 0
	v_add_u32_e32 v211, 0, v21
	v_readlane_b32 s20, v248, 5
	v_readlane_b32 s46, v248, 3
	s_barrier
	s_branch .LBB0_372
